# HGRN pass-3 item: next-item k-row prefetch addressed by a stepped scalar base and one lane offset instead of 64-bit VALU add pairs
# speedup vs baseline: 1.0002x; 1.0002x over previous
; DEV void hg_load_k(const u16* __restrict__ zb, int tid, u16 (&kr)[16]) {
;   const int wid = tid >> 6, lane = tid & 63, dir = wid >> 2, qu = wid & 3;
;   const u16* kp = zb + (long)(qu * 16) * NINP + C_HF + dir * 512 + lane;
; #pragma unroll
;   for (int i = 0; i < 16; ++i) kr[i] = kp[(long)i * NINP];
; }
.LBB0_1048:
	s_mul_hi_i32 s12, s75, 0x38e38e39
	s_lshr_b32 s13, s12, 31
	s_ashr_i32 s12, s12, 3
	s_add_i32 s12, s12, s13
	s_mul_i32 s13, s12, 36
	s_sub_i32 s13, s75, s13
	s_ashr_i32 s18, s12, 3
	s_lshl_b32 s13, s13, 6
	s_mul_hi_i32 s19, s18, 0x900
	s_mulk_i32 s18, 0x900
	s_ashr_i32 s71, s13, 31
	s_add_u32 s13, s18, s13
	s_addc_u32 s18, s19, s71
	s_mulk_i32 s18, 0x4400
	s_mul_hi_u32 s19, s13, 0x4400
	s_add_i32 s19, s19, s18
	s_mulk_i32 s13, 0x4400
	s_add_u32 s13, s88, s13
	s_addc_u32 s18, s89, s19
	s_lshl_b32 s12, s12, 7
	s_and_b32 s12, s12, 0x380
	s_add_u32 s12, s13, s12
	s_addc_u32 s13, s18, 0
	v_readlane_b32 s18, v255, 40
	v_readlane_b32 s19, v255, 41
	v_lshlrev_b32_e32 v0, 1, v68
	v_mov_b32_e32 v1, v157
	v_lshl_add_u32 v2, v70, 1, v156
	v_add_u32_e32 v2, v2, v0
	s_and_b32 s71, s24, 7
	global_load_ushort v109, v2, s[12:13] offset:3904
	s_add_u32 s12, s12, 0x4400
	s_addc_u32 s13, s13, 0
	global_load_ushort v110, v2, s[12:13] offset:3904
	s_add_u32 s12, s12, 0x4400
	s_addc_u32 s13, s13, 0
	global_load_ushort v111, v2, s[12:13] offset:3904
	s_add_u32 s12, s12, 0x4400
	s_addc_u32 s13, s13, 0
	global_load_ushort v112, v2, s[12:13] offset:3904
	s_add_u32 s12, s12, 0x4400
	s_addc_u32 s13, s13, 0
	global_load_ushort v113, v2, s[12:13] offset:3904
	s_add_u32 s12, s12, 0x4400
	s_addc_u32 s13, s13, 0
	global_load_ushort v114, v2, s[12:13] offset:3904
	s_add_u32 s12, s12, 0x4400
	s_addc_u32 s13, s13, 0
	global_load_ushort v115, v2, s[12:13] offset:3904
	s_add_u32 s12, s12, 0x4400
	s_addc_u32 s13, s13, 0
	global_load_ushort v116, v2, s[12:13] offset:3904
	s_add_u32 s12, s12, 0x4400
	s_addc_u32 s13, s13, 0
	global_load_ushort v117, v2, s[12:13] offset:3904
	s_add_u32 s12, s12, 0x4400
	s_addc_u32 s13, s13, 0
	global_load_ushort v118, v2, s[12:13] offset:3904
	s_add_u32 s12, s12, 0x4400
	s_addc_u32 s13, s13, 0
	global_load_ushort v119, v2, s[12:13] offset:3904
	s_add_u32 s12, s12, 0x4400
	s_addc_u32 s13, s13, 0
	global_load_ushort v120, v2, s[12:13] offset:3904
	s_add_u32 s12, s12, 0x4400
	s_addc_u32 s13, s13, 0
	global_load_ushort v121, v2, s[12:13] offset:3904
	s_add_u32 s12, s12, 0x4400
	s_addc_u32 s13, s13, 0
	global_load_ushort v122, v2, s[12:13] offset:3904
	s_add_u32 s12, s12, 0x4400
	s_addc_u32 s13, s13, 0
	global_load_ushort v123, v2, s[12:13] offset:3904
	s_add_u32 s12, s12, 0x4400
	s_addc_u32 s13, s13, 0
	global_load_ushort v124, v2, s[12:13] offset:3904
	s_mov_b64 s[12:13], -1
	s_and_b64 vcc, exec, s[18:19]
	s_cbranch_vccz .LBB0_1050
	s_ashr_i32 s12, s24, 3
	s_mul_hi_i32 s13, s12, 0x38e38e39
	s_lshr_b32 s18, s13, 31
	s_ashr_i32 s13, s13, 3
	s_add_i32 s13, s13, s18
	s_lshl_b32 s18, s13, 3
	s_or_b32 s18, s18, s71
	s_mul_i32 s13, s13, 36
	s_mul_i32 s18, s18, 36
	s_sub_i32 s12, s12, s13
	s_add_i32 s74, s18, s12
	s_mov_b64 s[12:13], 0
